# attention tile loop: static s_setprio 1 for the non-deferred wave group (waves 0-3)
# speedup vs baseline: 1.0072x; 1.0072x over previous
; #define LAS __attribute__((address_space(3)))
; DEV void attn_item(LAS unsigned char* lds, const bf16_t* P, const bf16_t* QB, const bf16_t* KV, const bf16_t* KC, const bf16_t* VC, const float* rel_bias, bf16_t* OB, int b, int g, int qt) {
;     ...
;         const int cur = qt;
;         const unsigned forced = 1u | (1u << cur) | (cur > 0 ? (1u << (cur - 1)) : 0u);
;         const int need = 8 - __popc(forced);
;         for (int it = 0; it < 4; ++it) { const int q = wave * 8 + it * 2 + (lane >> 5), j = lane & 31;
;             const float v = IMPF[q * 32 + j]; int rank = 0;
;             for (int jp = 1; jp <= cur - 2; ++jp) { const float vp = IMPF[q * 32 + jp]; rank += (vp > v || (vp == v && jp < j)) ? 1 : 0; }
;             const bool sel = (j >= 1) && (j <= cur - 2) && (rank < need);
;             const unsigned long long bal = __ballot(sel);
;             const unsigned mq = forced | (unsigned)(lane < 32 ? bal : (bal >> 32));
;             if (j == 0) MASK[q] = mq; }
;     }
;     __syncthreads();
;     const unsigned mymask = MASK[qs * 16 + fr];
;     unsigned anym = MASK[lane];
; #pragma unroll
;     for (int o = 32; o >= 1; o >>= 1) anym |= __shfl_xor(anym, o);
;     anym = __builtin_amdgcn_readfirstlane(anym);
;     {
;         float cbias[2]; cbias[0] = *(const LAS float*)(lds + btb + 512); cbias[1] = *(const LAS float*)(lds + btb + 512 + 516);
;         float mrun[2] = {NEG_, NEG_}, lrun[2] = {0.f, 0.f}; f32x4 O[2][4];
; #pragma unroll
;         for (int hh = 0; hh < 2; ++hh)
; #pragma unroll
;             for (int dt = 0; dt < 4; ++dt) O[hh][dt] = (f32x4){0.f, 0.f, 0.f, 0.f};
;         unsigned rem = anym & (qt >= 31 ? 0xffffffffu : ((2u << qt) - 1u)); rem &= ~1u;
;         int mode = 1, j = 0, buf = 0;
;         for (;;) {
;             kv_store(lds, pre, buf, tid);
.Lrk_done:
	s_lshr_b32 s4, 0x80000000, s17
	s_lshl_b32 s5, 1, s64
	s_cmp_lg_u32 s17, 31
	s_cselect_b32 s5, s5, 0
	s_or_b32 s4, s4, s5
	s_or_b32 s92, s4, 1
	s_bcnt1_i32_b32 s4, s92
	s_sub_i32 s93, 8, s4
	v_cmp_ne_u32_e32 vcc, 0, v60
	v_cmp_ge_i32_e64 s[44:45], s36, v60
	v_and_b32_e32 v67, 32, v150
	v_lshl_add_u32 v68, v66, 2, 0
	s_and_b64 s[4:5], vcc, s[44:45]
	v_add_u32_e32 v68, 0x11c00, v68
	v_cmp_eq_u32_e64 s[42:43], 0, v60
	v_cmp_gt_i32_e32 vcc, s93, v74
	s_and_b64 vcc, s[4:5], vcc
	s_nop 0
	v_lshrrev_b64 v[78:79], v67, vcc
	v_or_b32_e32 v78, s92, v78
	v_cmp_gt_i32_e32 vcc, s93, v75
	s_and_b64 vcc, s[4:5], vcc
	s_nop 0
	v_lshrrev_b64 v[80:81], v67, vcc
	v_or_b32_e32 v80, s92, v80
	v_cmp_gt_i32_e32 vcc, s93, v76
	s_and_b64 vcc, s[4:5], vcc
	s_nop 0
	v_lshrrev_b64 v[82:83], v67, vcc
	v_or_b32_e32 v82, s92, v82
	v_cmp_gt_i32_e32 vcc, s93, v77
	s_and_b64 vcc, s[4:5], vcc
	s_nop 0
	v_lshrrev_b64 v[84:85], v67, vcc
	v_or_b32_e32 v84, s92, v84
	s_and_saveexec_b64 s[4:5], s[42:43]
	ds_write_b32 v68, v78
	ds_write_b32 v68, v80 offset:8
	ds_write_b32 v68, v82 offset:16
	ds_write_b32 v68, v84 offset:24
	s_or_b64 exec, exec, s[4:5]
	s_add_i32 s4, 0, 0x11c00
	v_lshl_add_u32 v7, v152, 2, s4
	s_waitcnt lgkmcnt(0)
	s_barrier
	ds_read_b32 v7, v7
	v_lshlrev_b32_e32 v60, 2, v137
	v_lshlrev_b32_e32 v61, 2, v136
	v_add3_u32 v60, s4, v60, v61
	ds_read_b32 v127, v60
	s_waitcnt lgkmcnt(1)
	ds_bpermute_b32 v61, v144, v7
	v_and_b32_e32 v60, 0xffff0000, v149
	v_lshlrev_b32_e32 v126, 16, v149
	s_lshl_b32 s5, 2, s15
	s_waitcnt lgkmcnt(1)
	v_pk_fma_f32 v[134:135], v[126:127], v[2:3], 0 op_sel_hi:[0,1,0]
	s_waitcnt lgkmcnt(0)
	v_or_b32_e32 v7, v61, v7
	v_pk_fma_f32 v[116:117], v[60:61], v[44:45], 0 op_sel_hi:[0,1,0]
	ds_bpermute_b32 v44, v143, v7
	v_xor_b32_e32 v3, 4, v213
	v_pk_fma_f32 v[130:131], v[126:127], v[4:5], 0 op_sel_hi:[0,1,0]
	v_pk_fma_f32 v[132:133], v[126:127], v[32:33], 0 op_sel_hi:[0,1,0]
	s_add_i32 s5, s5, -1
	s_waitcnt lgkmcnt(0)
	v_or_b32_e32 v7, v44, v7
	v_xor_b32_e32 v44, 8, v213
	v_cmp_lt_i32_e32 vcc, v44, v153
	s_and_b32 s5, s5, -2
	s_cmp_lt_u32 s15, 31
	v_cndmask_b32_e32 v44, v213, v44, vcc
	v_lshlrev_b32_e32 v44, 2, v44
	ds_bpermute_b32 v44, v44, v7
	v_cmp_lt_i32_e32 vcc, v3, v153
	s_cselect_b32 s5, s5, -2
	v_pk_fma_f32 v[114:115], v[60:61], v[46:47], 0 op_sel_hi:[0,1,0]
	v_cndmask_b32_e32 v3, v213, v3, vcc
	s_waitcnt lgkmcnt(0)
	v_or_b32_e32 v2, v44, v7
	v_lshlrev_b32_e32 v3, 2, v3
	ds_bpermute_b32 v3, v3, v2
	v_pk_fma_f32 v[110:111], v[60:61], v[50:51], 0 op_sel_hi:[0,1,0]
	v_pk_fma_f32 v[112:113], v[60:61], v[48:49], 0 op_sel_hi:[0,1,0]
	v_pk_fma_f32 v[104:105], v[60:61], v[54:55], 0 op_sel_hi:[0,1,0]
	v_pk_fma_f32 v[108:109], v[60:61], v[52:53], 0 op_sel_hi:[0,1,0]
	s_waitcnt lgkmcnt(0)
	v_or_b32_e32 v4, v3, v2
	v_xor_b32_e32 v2, 2, v213
	v_cmp_lt_i32_e32 vcc, v2, v153
	v_and_b32_e32 v3, 0xffff0000, v148
	v_pk_fma_f32 v[102:103], v[60:61], v[58:59], 0 op_sel_hi:[0,1,0]
	v_cndmask_b32_e32 v2, v213, v2, vcc
	v_lshlrev_b32_e32 v2, 2, v2
	ds_bpermute_b32 v5, v2, v4
	v_lshlrev_b32_e32 v2, 16, v148
	v_mov_b32_e32 v148, 0
	v_pk_fma_f32 v[106:107], v[60:61], v[56:57], 0 op_sel_hi:[0,1,0]
	v_pk_fma_f32 v[128:129], v[126:127], v[34:35], 0 op_sel_hi:[0,1,0]
	s_waitcnt lgkmcnt(0)
	v_or_b32_e32 v32, v5, v4
	v_xor_b32_e32 v4, 1, v213
	v_cmp_lt_i32_e32 vcc, v4, v153
	v_pk_fma_f32 v[120:121], v[126:127], v[38:39], 0 op_sel_hi:[0,1,0]
	v_pk_fma_f32 v[124:125], v[126:127], v[36:37], 0 op_sel_hi:[0,1,0]
	v_cndmask_b32_e32 v4, v213, v4, vcc
	v_lshlrev_b32_e32 v4, 2, v4
	ds_bpermute_b32 v33, v4, v32
	v_pk_fma_f32 v[118:119], v[126:127], v[42:43], 0 op_sel_hi:[0,1,0]
	v_pk_fma_f32 v[122:123], v[126:127], v[40:41], 0 op_sel_hi:[0,1,0]
	v_and_b32_e32 v5, 0xffff0000, v147
	v_lshlrev_b32_e32 v4, 16, v147
	s_waitcnt lgkmcnt(0)
	v_or_b32_e32 v32, v33, v32
	v_add_u32_e32 v33, 0x200, v142
	ds_read2_b32 v[136:137], v33 offset1:129
	v_readfirstlane_b32 s4, v32
	v_mul_lo_u32 v32, v100, s24
	v_or_b32_e32 v32, v32, v152
	v_lshl_add_u32 v146, v32, 1, v221
	v_sub_u32_e64 v32, s15, 8 clamp
	v_mov_b32_e32 v7, v60
	s_mov_b32 s97, 1
	s_and_b32 s95, s4, s5
	v_readfirstlane_b32 s94, v32
	s_sub_i32 s17, 23, s17
	v_add_u32_e32 v145, 0, v145
	s_mov_b32 s50, 0
	v_mov_b32_e32 v150, 0xf149f2ca
	v_mov_b32_e32 v147, 0
	v_mov_b32_e32 v149, 0xf149f2ca
	v_mov_b32_e32 v151, 0
	v_mov_b32_e32 v48, 0
	v_mov_b32_e32 v49, v148
	v_mov_b32_e32 v50, v148
	v_mov_b32_e32 v51, v148
	v_mov_b32_e32 v36, 0
	v_mov_b32_e32 v37, v148
	v_mov_b32_e32 v38, v148
	v_mov_b32_e32 v39, v148
	v_mov_b32_e32 v40, 0
	v_mov_b32_e32 v41, v148
	v_mov_b32_e32 v42, v148
	v_mov_b32_e32 v43, v148
	v_mov_b32_e32 v32, 0
	v_mov_b32_e32 v33, v148
	v_mov_b32_e32 v34, v148
	v_mov_b32_e32 v35, v148
	v_mov_b32_e32 v60, 0
	v_mov_b32_e32 v61, v148
	v_mov_b32_e32 v62, v148
	v_mov_b32_e32 v63, v148
	v_mov_b32_e32 v52, 0
	v_mov_b32_e32 v53, v148
	v_mov_b32_e32 v54, v148
	v_mov_b32_e32 v55, v148
	v_mov_b32_e32 v56, 0
	v_mov_b32_e32 v57, v148
	v_mov_b32_e32 v58, v148
	v_mov_b32_e32 v59, v148
	v_mov_b32_e32 v44, 0
	v_mov_b32_e32 v45, v148
	v_mov_b32_e32 v46, v148
	v_mov_b32_e32 v47, v148
	v_readfirstlane_b32 s100, v210
	s_mov_b32 s98, 0
	s_waitcnt vmcnt(1)
	ds_write_b128 v139, v[24:27]
	s_waitcnt vmcnt(0)
	ds_write_b16 v146, v28
	ds_write_b16_d16_hi v146, v28 offset:144
	ds_write_b16 v146, v29 offset:288
	ds_write_b16_d16_hi v146, v29 offset:432
	ds_write_b16 v146, v30 offset:576
	ds_write_b16_d16_hi v146, v30 offset:720
	ds_write_b16 v146, v31 offset:864
	ds_write_b16_d16_hi v146, v31 offset:1008
	s_lshr_b32 s100, s100, 8
	s_mul_i32 s100, s100, 3
	s_cmp_eq_u32 s100, 0
	s_cbranch_scc0 .Lpr_skip
	s_setprio 1
